# P10 + P5 epilogues: rolling 8-deep prefetch of residual/gate loads with counted vmcnt instead of per-step vmcnt(0) (on top of P9 hoist)
# baseline (speedup 1.0000x reference)
.LBB0_989:
	v_lshl_add_u32 v150, s22, 8, v152
	v_lshl_or_b32 v148, s44, 8, v154
	v_ashrrev_i32_e32 v151, 31, v150
	v_lshlrev_b64 v[158:159], 13, v[150:151]
	v_ashrrev_i32_e32 v149, 31, v148
	v_lshl_add_u64 v[158:159], s[64:65], 0, v[158:159]
	v_lshlrev_b64 v[148:149], 1, v[148:149]
	v_lshl_add_u64 v[162:163], v[158:159], 0, v[148:149]
	v_mov_b32_e32 v228, 0x20000
	v_mov_b32_e32 v229, 0
	v_lshl_add_u64 v[222:223], v[162:163], 0, v[228:229]
	v_lshl_add_u64 v[224:225], v[222:223], 0, v[228:229]
	v_lshl_add_u64 v[226:227], v[224:225], 0, v[228:229]
	global_load_dwordx4 v[190:193], v[162:163], off
	global_load_dwordx4 v[194:197], v[162:163], off offset:256
	global_load_dwordx4 v[198:201], v[222:223], off
	global_load_dwordx4 v[202:205], v[222:223], off offset:256
	global_load_dwordx4 v[206:209], v[224:225], off
	global_load_dwordx4 v[210:213], v[224:225], off offset:256
	global_load_dwordx4 v[214:217], v[226:227], off
	global_load_dwordx4 v[218:221], v[226:227], off offset:256
	v_lshl_add_u64 v[222:223], v[228:229], 3, v[162:163]
	v_lshl_add_u64 v[224:225], v[222:223], 0, v[228:229]
	v_lshl_add_u64 v[226:227], v[224:225], 0, v[228:229]
	v_lshl_add_u64 v[228:229], v[226:227], 0, v[228:229]
	v_lshlrev_b64 v[164:165], 12, v[150:151]
	v_lshl_add_u64 v[164:165], s[54:55], 0, v[164:165]
	v_lshl_add_u64 v[164:165], v[164:165], 0, v[148:149]
	s_andn2_b64 vcc, exec, s[0:1]
	s_mov_b64 s[0:1], -1
	s_waitcnt vmcnt(7)
	v_lshlrev_b32_e32 v166, 16, v190
	v_and_b32_e32 v167, 0xffff0000, v190
	v_lshlrev_b32_e32 v158, 16, v191
	v_and_b32_e32 v159, 0xffff0000, v191
	v_lshlrev_b32_e32 v168, 16, v192
	v_and_b32_e32 v169, 0xffff0000, v192
	v_lshlrev_b32_e32 v160, 16, v193
	v_and_b32_e32 v161, 0xffff0000, v193
	global_load_dwordx4 v[190:193], v[222:223], off
	v_pk_mul_f32 v[126:127], v[126:127], v[166:167]
	v_pk_mul_f32 v[128:129], v[128:129], v[158:159]
	v_pk_mul_f32 v[158:159], v[122:123], v[168:169]
	v_pk_mul_f32 v[160:161], v[124:125], v[160:161]
	v_cvt_pk_bf16_f32 v122, v126, v127
	v_cvt_pk_bf16_f32 v123, v128, v129
	v_cvt_pk_bf16_f32 v124, v158, v159
	v_cvt_pk_bf16_f32 v125, v160, v161
	global_store_dwordx4 v[164:165], v[122:125], off
	s_nop 0
	v_or_b32_e32 v126, 16, v150
	v_ashrrev_i32_e32 v127, 31, v126
	v_lshlrev_b64 v[128:129], 13, v[126:127]
	v_lshl_add_u64 v[128:129], s[64:65], 0, v[128:129]
	v_lshl_add_u64 v[128:129], v[128:129], 0, v[148:149]
	s_waitcnt vmcnt(8)
	v_lshlrev_b32_e32 v158, 16, v194
	v_and_b32_e32 v159, 0xffff0000, v194
	v_lshlrev_b32_e32 v122, 16, v195
	v_and_b32_e32 v123, 0xffff0000, v195
	v_lshlrev_b32_e32 v160, 16, v196
	v_and_b32_e32 v161, 0xffff0000, v196
	v_lshlrev_b32_e32 v124, 16, v197
	v_and_b32_e32 v125, 0xffff0000, v197
	global_load_dwordx4 v[194:197], v[222:223], off offset:256
	v_pk_mul_f32 v[118:119], v[118:119], v[158:159]
	v_pk_mul_f32 v[120:121], v[120:121], v[122:123]
	v_pk_mul_f32 v[122:123], v[114:115], v[160:161]
	v_pk_mul_f32 v[124:125], v[116:117], v[124:125]
	v_cvt_pk_bf16_f32 v114, v118, v119
	v_cvt_pk_bf16_f32 v115, v120, v121
	v_cvt_pk_bf16_f32 v116, v122, v123
	v_cvt_pk_bf16_f32 v117, v124, v125
	global_store_dwordx4 v[164:165], v[114:117], off offset:256
	s_nop 0
	v_lshlrev_b64 v[118:119], 12, v[126:127]
	v_lshl_add_u64 v[118:119], s[54:55], 0, v[118:119]
	v_lshl_add_u64 v[118:119], v[118:119], 0, v[148:149]
	s_waitcnt vmcnt(9)
	v_lshlrev_b32_e32 v120, 16, v198
	v_and_b32_e32 v121, 0xffff0000, v198
	v_lshlrev_b32_e32 v114, 16, v199
	v_and_b32_e32 v115, 0xffff0000, v199
	v_lshlrev_b32_e32 v122, 16, v200
	v_and_b32_e32 v123, 0xffff0000, v200
	v_lshlrev_b32_e32 v116, 16, v201
	v_and_b32_e32 v117, 0xffff0000, v201
	global_load_dwordx4 v[198:201], v[224:225], off
	v_pk_mul_f32 v[110:111], v[110:111], v[120:121]
	v_pk_mul_f32 v[112:113], v[112:113], v[114:115]
	v_pk_mul_f32 v[114:115], v[106:107], v[122:123]
	v_pk_mul_f32 v[116:117], v[108:109], v[116:117]
	v_cvt_pk_bf16_f32 v106, v110, v111
	v_cvt_pk_bf16_f32 v107, v112, v113
	v_cvt_pk_bf16_f32 v108, v114, v115
	v_cvt_pk_bf16_f32 v109, v116, v117
	global_store_dwordx4 v[118:119], v[106:109], off
	s_nop 0
	v_or_b32_e32 v110, 32, v150
	v_ashrrev_i32_e32 v111, 31, v110
	v_lshlrev_b64 v[112:113], 13, v[110:111]
	v_lshl_add_u64 v[112:113], s[64:65], 0, v[112:113]
	v_lshl_add_u64 v[112:113], v[112:113], 0, v[148:149]
	s_waitcnt vmcnt(10)
	v_lshlrev_b32_e32 v114, 16, v202
	v_and_b32_e32 v115, 0xffff0000, v202
	v_lshlrev_b32_e32 v106, 16, v203
	v_and_b32_e32 v107, 0xffff0000, v203
	v_lshlrev_b32_e32 v116, 16, v204
	v_and_b32_e32 v117, 0xffff0000, v204
	v_lshlrev_b32_e32 v108, 16, v205
	v_and_b32_e32 v109, 0xffff0000, v205
	global_load_dwordx4 v[202:205], v[224:225], off offset:256
	v_pk_mul_f32 v[102:103], v[102:103], v[114:115]
	v_pk_mul_f32 v[104:105], v[104:105], v[106:107]
	v_pk_mul_f32 v[106:107], v[98:99], v[116:117]
	v_pk_mul_f32 v[108:109], v[100:101], v[108:109]
	v_cvt_pk_bf16_f32 v98, v102, v103
	v_cvt_pk_bf16_f32 v99, v104, v105
	v_cvt_pk_bf16_f32 v100, v106, v107
	v_cvt_pk_bf16_f32 v101, v108, v109
	global_store_dwordx4 v[118:119], v[98:101], off offset:256
	s_nop 0
	v_lshlrev_b64 v[102:103], 12, v[110:111]
	v_lshl_add_u64 v[102:103], s[54:55], 0, v[102:103]
	v_lshl_add_u64 v[102:103], v[102:103], 0, v[148:149]
	s_waitcnt vmcnt(11)
	v_lshlrev_b32_e32 v104, 16, v206
	v_and_b32_e32 v105, 0xffff0000, v206
	v_lshlrev_b32_e32 v98, 16, v207
	v_and_b32_e32 v99, 0xffff0000, v207
	v_lshlrev_b32_e32 v106, 16, v208
	v_and_b32_e32 v107, 0xffff0000, v208
	v_lshlrev_b32_e32 v100, 16, v209
	v_and_b32_e32 v101, 0xffff0000, v209
	global_load_dwordx4 v[206:209], v[226:227], off
	v_pk_mul_f32 v[94:95], v[94:95], v[104:105]
	v_pk_mul_f32 v[96:97], v[96:97], v[98:99]
	v_pk_mul_f32 v[98:99], v[90:91], v[106:107]
	v_pk_mul_f32 v[100:101], v[92:93], v[100:101]
	v_cvt_pk_bf16_f32 v90, v94, v95
	v_cvt_pk_bf16_f32 v91, v96, v97
	v_cvt_pk_bf16_f32 v92, v98, v99
	v_cvt_pk_bf16_f32 v93, v100, v101
	global_store_dwordx4 v[102:103], v[90:93], off
	s_nop 0
	v_or_b32_e32 v94, 48, v150
	v_ashrrev_i32_e32 v95, 31, v94
	v_lshlrev_b64 v[96:97], 13, v[94:95]
	v_lshl_add_u64 v[96:97], s[64:65], 0, v[96:97]
	v_lshl_add_u64 v[96:97], v[96:97], 0, v[148:149]
	s_waitcnt vmcnt(12)
	v_lshlrev_b32_e32 v98, 16, v210
	v_and_b32_e32 v99, 0xffff0000, v210
	v_lshlrev_b32_e32 v90, 16, v211
	v_and_b32_e32 v91, 0xffff0000, v211
	v_lshlrev_b32_e32 v100, 16, v212
	v_and_b32_e32 v101, 0xffff0000, v212
	v_lshlrev_b32_e32 v92, 16, v213
	v_and_b32_e32 v93, 0xffff0000, v213
	global_load_dwordx4 v[210:213], v[226:227], off offset:256
	v_pk_mul_f32 v[86:87], v[86:87], v[98:99]
	v_pk_mul_f32 v[88:89], v[88:89], v[90:91]
	v_pk_mul_f32 v[90:91], v[82:83], v[100:101]
	v_pk_mul_f32 v[92:93], v[84:85], v[92:93]
	v_cvt_pk_bf16_f32 v82, v86, v87
	v_cvt_pk_bf16_f32 v83, v88, v89
	v_cvt_pk_bf16_f32 v84, v90, v91
	v_cvt_pk_bf16_f32 v85, v92, v93
	global_store_dwordx4 v[102:103], v[82:85], off offset:256
	s_nop 0
	v_lshlrev_b64 v[86:87], 12, v[94:95]
	v_lshl_add_u64 v[86:87], s[54:55], 0, v[86:87]
	v_lshl_add_u64 v[86:87], v[86:87], 0, v[148:149]
	s_waitcnt vmcnt(13)
	v_lshlrev_b32_e32 v88, 16, v214
	v_and_b32_e32 v89, 0xffff0000, v214
	v_lshlrev_b32_e32 v82, 16, v215
	v_and_b32_e32 v83, 0xffff0000, v215
	v_lshlrev_b32_e32 v90, 16, v216
	v_and_b32_e32 v91, 0xffff0000, v216
	v_lshlrev_b32_e32 v84, 16, v217
	v_and_b32_e32 v85, 0xffff0000, v217
	global_load_dwordx4 v[214:217], v[228:229], off
	v_pk_mul_f32 v[78:79], v[78:79], v[88:89]
	v_pk_mul_f32 v[80:81], v[80:81], v[82:83]
	v_pk_mul_f32 v[82:83], v[74:75], v[90:91]
	v_pk_mul_f32 v[84:85], v[76:77], v[84:85]
	v_cvt_pk_bf16_f32 v74, v78, v79
	v_cvt_pk_bf16_f32 v75, v80, v81
	v_cvt_pk_bf16_f32 v76, v82, v83
	v_cvt_pk_bf16_f32 v77, v84, v85
	global_store_dwordx4 v[86:87], v[74:77], off
	s_nop 0
	v_add_u32_e32 v78, 0x80, v150
	v_ashrrev_i32_e32 v79, 31, v78
	v_lshlrev_b64 v[80:81], 13, v[78:79]
	v_lshl_add_u64 v[80:81], s[64:65], 0, v[80:81]
	v_lshl_add_u64 v[80:81], v[80:81], 0, v[148:149]
	s_waitcnt vmcnt(14)
	v_lshlrev_b32_e32 v82, 16, v218
	v_and_b32_e32 v83, 0xffff0000, v218
	v_lshlrev_b32_e32 v74, 16, v219
	v_and_b32_e32 v75, 0xffff0000, v219
	v_lshlrev_b32_e32 v84, 16, v220
	v_and_b32_e32 v85, 0xffff0000, v220
	v_lshlrev_b32_e32 v76, 16, v221
	v_and_b32_e32 v77, 0xffff0000, v221
	global_load_dwordx4 v[218:221], v[228:229], off offset:256
	v_pk_mul_f32 v[70:71], v[70:71], v[82:83]
	v_pk_mul_f32 v[72:73], v[72:73], v[74:75]
	v_pk_mul_f32 v[74:75], v[66:67], v[84:85]
	v_pk_mul_f32 v[76:77], v[68:69], v[76:77]
	v_cvt_pk_bf16_f32 v66, v70, v71
	v_cvt_pk_bf16_f32 v67, v72, v73
	v_cvt_pk_bf16_f32 v68, v74, v75
	v_cvt_pk_bf16_f32 v69, v76, v77
	global_store_dwordx4 v[86:87], v[66:69], off offset:256
	s_nop 0
	v_lshlrev_b64 v[70:71], 12, v[78:79]
	v_lshl_add_u64 v[70:71], s[54:55], 0, v[70:71]
	v_lshl_add_u64 v[70:71], v[70:71], 0, v[148:149]
	s_waitcnt vmcnt(15)
	v_lshlrev_b32_e32 v72, 16, v190
	v_and_b32_e32 v73, 0xffff0000, v190
	v_lshlrev_b32_e32 v66, 16, v191
	v_and_b32_e32 v67, 0xffff0000, v191
	v_lshlrev_b32_e32 v74, 16, v192
	v_and_b32_e32 v75, 0xffff0000, v192
	v_lshlrev_b32_e32 v68, 16, v193
	v_and_b32_e32 v69, 0xffff0000, v193
	v_pk_mul_f32 v[62:63], v[62:63], v[72:73]
	v_pk_mul_f32 v[64:65], v[64:65], v[66:67]
	v_pk_mul_f32 v[66:67], v[58:59], v[74:75]
	v_pk_mul_f32 v[68:69], v[60:61], v[68:69]
	v_cvt_pk_bf16_f32 v58, v62, v63
	v_cvt_pk_bf16_f32 v59, v64, v65
	v_cvt_pk_bf16_f32 v60, v66, v67
	v_cvt_pk_bf16_f32 v61, v68, v69
	global_store_dwordx4 v[70:71], v[58:61], off
	s_nop 0
	v_add_u32_e32 v62, 0x90, v150
	v_ashrrev_i32_e32 v63, 31, v62
	v_lshlrev_b64 v[64:65], 13, v[62:63]
	v_lshl_add_u64 v[64:65], s[64:65], 0, v[64:65]
	v_lshl_add_u64 v[64:65], v[64:65], 0, v[148:149]
	s_waitcnt vmcnt(14)
	v_lshlrev_b32_e32 v66, 16, v194
	v_and_b32_e32 v67, 0xffff0000, v194
	v_lshlrev_b32_e32 v58, 16, v195
	v_and_b32_e32 v59, 0xffff0000, v195
	v_lshlrev_b32_e32 v68, 16, v196
	v_and_b32_e32 v69, 0xffff0000, v196
	v_lshlrev_b32_e32 v60, 16, v197
	v_and_b32_e32 v61, 0xffff0000, v197
	v_pk_mul_f32 v[54:55], v[54:55], v[66:67]
	v_pk_mul_f32 v[56:57], v[56:57], v[58:59]
	v_pk_mul_f32 v[58:59], v[50:51], v[68:69]
	v_pk_mul_f32 v[60:61], v[52:53], v[60:61]
	v_cvt_pk_bf16_f32 v50, v54, v55
	v_cvt_pk_bf16_f32 v51, v56, v57
	v_cvt_pk_bf16_f32 v52, v58, v59
	v_cvt_pk_bf16_f32 v53, v60, v61
	global_store_dwordx4 v[70:71], v[50:53], off offset:256
	s_nop 0
	v_lshlrev_b64 v[54:55], 12, v[62:63]
	v_lshl_add_u64 v[54:55], s[54:55], 0, v[54:55]
	v_lshl_add_u64 v[54:55], v[54:55], 0, v[148:149]
	s_waitcnt vmcnt(13)
	v_lshlrev_b32_e32 v56, 16, v198
	v_and_b32_e32 v57, 0xffff0000, v198
	v_lshlrev_b32_e32 v50, 16, v199
	v_and_b32_e32 v51, 0xffff0000, v199
	v_lshlrev_b32_e32 v58, 16, v200
	v_and_b32_e32 v59, 0xffff0000, v200
	v_lshlrev_b32_e32 v52, 16, v201
	v_and_b32_e32 v53, 0xffff0000, v201
	v_pk_mul_f32 v[46:47], v[46:47], v[56:57]
	v_pk_mul_f32 v[48:49], v[48:49], v[50:51]
	v_pk_mul_f32 v[50:51], v[42:43], v[58:59]
	v_pk_mul_f32 v[52:53], v[44:45], v[52:53]
	v_cvt_pk_bf16_f32 v42, v46, v47
	v_cvt_pk_bf16_f32 v43, v48, v49
	v_cvt_pk_bf16_f32 v44, v50, v51
	v_cvt_pk_bf16_f32 v45, v52, v53
	global_store_dwordx4 v[54:55], v[42:45], off
	s_nop 0
	v_add_u32_e32 v46, 0xa0, v150
	v_ashrrev_i32_e32 v47, 31, v46
	v_lshlrev_b64 v[48:49], 13, v[46:47]
	v_lshl_add_u64 v[48:49], s[64:65], 0, v[48:49]
	v_lshl_add_u64 v[48:49], v[48:49], 0, v[148:149]
	s_waitcnt vmcnt(12)
	v_lshlrev_b32_e32 v50, 16, v202
	v_and_b32_e32 v51, 0xffff0000, v202
	v_lshlrev_b32_e32 v42, 16, v203
	v_and_b32_e32 v43, 0xffff0000, v203
	v_lshlrev_b32_e32 v52, 16, v204
	v_and_b32_e32 v53, 0xffff0000, v204
	v_lshlrev_b32_e32 v44, 16, v205
	v_and_b32_e32 v45, 0xffff0000, v205
	v_pk_mul_f32 v[38:39], v[38:39], v[50:51]
	v_pk_mul_f32 v[40:41], v[40:41], v[42:43]
	v_pk_mul_f32 v[42:43], v[34:35], v[52:53]
	v_pk_mul_f32 v[44:45], v[36:37], v[44:45]
	v_cvt_pk_bf16_f32 v34, v38, v39
	v_cvt_pk_bf16_f32 v35, v40, v41
	v_cvt_pk_bf16_f32 v36, v42, v43
	v_cvt_pk_bf16_f32 v37, v44, v45
	global_store_dwordx4 v[54:55], v[34:37], off offset:256
	s_nop 0
	v_lshlrev_b64 v[38:39], 12, v[46:47]
	v_lshl_add_u64 v[38:39], s[54:55], 0, v[38:39]
	v_lshl_add_u64 v[38:39], v[38:39], 0, v[148:149]
	s_waitcnt vmcnt(11)
	v_lshlrev_b32_e32 v40, 16, v206
	v_and_b32_e32 v41, 0xffff0000, v206
	v_lshlrev_b32_e32 v34, 16, v207
	v_and_b32_e32 v35, 0xffff0000, v207
	v_lshlrev_b32_e32 v42, 16, v208
	v_and_b32_e32 v43, 0xffff0000, v208
	v_lshlrev_b32_e32 v36, 16, v209
	v_and_b32_e32 v37, 0xffff0000, v209
	v_pk_mul_f32 v[30:31], v[30:31], v[40:41]
	v_pk_mul_f32 v[32:33], v[32:33], v[34:35]
	v_pk_mul_f32 v[34:35], v[26:27], v[42:43]
	v_pk_mul_f32 v[36:37], v[28:29], v[36:37]
	v_cvt_pk_bf16_f32 v26, v30, v31
	v_cvt_pk_bf16_f32 v27, v32, v33
	v_cvt_pk_bf16_f32 v28, v34, v35
	v_cvt_pk_bf16_f32 v29, v36, v37
	global_store_dwordx4 v[38:39], v[26:29], off
	s_nop 0
	v_add_u32_e32 v30, 0xb0, v150
	v_ashrrev_i32_e32 v31, 31, v30
	v_lshlrev_b64 v[32:33], 13, v[30:31]
	v_lshl_add_u64 v[32:33], s[64:65], 0, v[32:33]
	v_lshl_add_u64 v[32:33], v[32:33], 0, v[148:149]
	s_waitcnt vmcnt(10)
	v_lshlrev_b32_e32 v34, 16, v210
	v_and_b32_e32 v35, 0xffff0000, v210
	v_lshlrev_b32_e32 v26, 16, v211
	v_and_b32_e32 v27, 0xffff0000, v211
	v_lshlrev_b32_e32 v36, 16, v212
	v_and_b32_e32 v37, 0xffff0000, v212
	v_lshlrev_b32_e32 v28, 16, v213
	v_and_b32_e32 v29, 0xffff0000, v213
	v_pk_mul_f32 v[22:23], v[22:23], v[34:35]
	v_pk_mul_f32 v[24:25], v[24:25], v[26:27]
	v_pk_mul_f32 v[26:27], v[18:19], v[36:37]
	v_pk_mul_f32 v[28:29], v[20:21], v[28:29]
	v_cvt_pk_bf16_f32 v18, v22, v23
	v_cvt_pk_bf16_f32 v19, v24, v25
	v_cvt_pk_bf16_f32 v20, v26, v27
	v_cvt_pk_bf16_f32 v21, v28, v29
	global_store_dwordx4 v[38:39], v[18:21], off offset:256
	s_nop 0
	v_lshlrev_b64 v[22:23], 12, v[30:31]
	v_lshl_add_u64 v[22:23], s[54:55], 0, v[22:23]
	v_lshl_add_u64 v[22:23], v[22:23], 0, v[148:149]
	s_waitcnt vmcnt(9)
	v_lshlrev_b32_e32 v24, 16, v214
	v_and_b32_e32 v25, 0xffff0000, v214
	v_lshlrev_b32_e32 v18, 16, v215
	v_and_b32_e32 v19, 0xffff0000, v215
	v_lshlrev_b32_e32 v26, 16, v216
	v_and_b32_e32 v27, 0xffff0000, v216
	v_lshlrev_b32_e32 v20, 16, v217
	v_and_b32_e32 v21, 0xffff0000, v217
	v_pk_mul_f32 v[14:15], v[14:15], v[24:25]
	v_pk_mul_f32 v[16:17], v[16:17], v[18:19]
	v_pk_mul_f32 v[18:19], v[10:11], v[26:27]
	v_pk_mul_f32 v[20:21], v[12:13], v[20:21]
	v_cvt_pk_bf16_f32 v10, v14, v15
	v_cvt_pk_bf16_f32 v11, v16, v17
	v_cvt_pk_bf16_f32 v12, v18, v19
	v_cvt_pk_bf16_f32 v13, v20, v21
	global_store_dwordx4 v[22:23], v[10:13], off
	s_nop 0
	s_waitcnt vmcnt(8)
	v_lshlrev_b32_e32 v14, 16, v218
	v_and_b32_e32 v15, 0xffff0000, v218
	v_lshlrev_b32_e32 v10, 16, v219
	v_and_b32_e32 v11, 0xffff0000, v219
	v_lshlrev_b32_e32 v16, 16, v220
	v_and_b32_e32 v17, 0xffff0000, v220
	v_lshlrev_b32_e32 v12, 16, v221
	v_and_b32_e32 v13, 0xffff0000, v221
	v_pk_mul_f32 v[6:7], v[6:7], v[14:15]
	v_pk_mul_f32 v[8:9], v[8:9], v[10:11]
	v_pk_mul_f32 v[10:11], v[2:3], v[16:17]
	v_pk_mul_f32 v[12:13], v[4:5], v[12:13]
	v_cvt_pk_bf16_f32 v2, v6, v7
	v_cvt_pk_bf16_f32 v3, v8, v9
	v_cvt_pk_bf16_f32 v4, v10, v11
	v_cvt_pk_bf16_f32 v5, v12, v13
	global_store_dwordx4 v[22:23], v[2:5], off offset:256
	s_cbranch_vccnz .LBB0_982
	s_andn2_b64 vcc, exec, s[2:3]
	s_cbranch_vccnz .LBB0_981
	s_barrier
	s_branch .LBB0_981

.LBB0_1287:
	s_lshl_b32 s27, s56, 8
	s_add_i32 s26, s27, 0xffffe000
	s_lshr_b32 s26, s26, 12
	s_add_i32 s26, s26, 1
	s_cmp_gt_i32 s56, 31
	s_cselect_b32 s26, s26, 0
	s_mul_hi_u32 s28, s26, 0xc000
	s_mul_i32 s26, s26, 0xc000
	v_add_u32_e32 v168, s27, v170
	v_lshl_or_b32 v122, s57, 8, v172
	s_add_u32 s26, s66, s26
	v_ashrrev_i32_e32 v169, 31, v168
	v_ashrrev_i32_e32 v123, 31, v122
	v_lshlrev_b64 v[166:167], 12, v[168:169]
	s_addc_u32 s27, s67, s28
	v_lshl_add_u64 v[124:125], s[64:65], 0, v[166:167]
	v_lshlrev_b64 v[164:165], 1, v[122:123]
	v_lshl_add_u64 v[122:123], v[122:123], 2, s[26:27]
	v_lshl_add_u64 v[176:177], v[124:125], 0, v[164:165]
	v_lshl_add_u64 v[124:125], v[122:123], 0, s[14:15]
	v_add_co_u32_e32 v122, vcc, s45, v122
	s_nop 0
	s_nop 0
	v_addc_co_u32_e32 v123, vcc, 0, v123, vcc
	global_load_dwordx4 v[130:133], v[124:125], off offset:16
	global_load_dwordx4 v[134:137], v[122:123], off
	v_lshl_add_u64 v[122:123], s[52:53], 0, v[166:167]
	v_lshl_add_u64 v[184:185], v[122:123], 0, v[164:165]
	global_load_dwordx4 v[126:129], v[124:125], off offset:512
	s_nop 0
	global_load_dwordx4 v[122:125], v[124:125], off offset:528
	v_mov_b32_e32 v228, 0x10000
	v_mov_b32_e32 v229, 0
	v_lshl_add_u64 v[222:223], v[176:177], 0, v[228:229]
	v_lshl_add_u64 v[224:225], v[222:223], 0, v[228:229]
	v_lshl_add_u64 v[226:227], v[224:225], 0, v[228:229]
	global_load_dwordx4 v[190:193], v[176:177], off
	global_load_dwordx4 v[194:197], v[176:177], off offset:256
	global_load_dwordx4 v[198:201], v[222:223], off
	global_load_dwordx4 v[202:205], v[222:223], off offset:256
	global_load_dwordx4 v[206:209], v[224:225], off
	global_load_dwordx4 v[210:213], v[224:225], off offset:256
	global_load_dwordx4 v[214:217], v[226:227], off
	global_load_dwordx4 v[218:221], v[226:227], off offset:256
	v_lshl_add_u64 v[222:223], v[228:229], 3, v[176:177]
	v_lshl_add_u64 v[224:225], v[222:223], 0, v[228:229]
	v_lshl_add_u64 v[226:227], v[224:225], 0, v[228:229]
	v_lshl_add_u64 v[228:229], v[226:227], 0, v[228:229]
	s_and_b64 vcc, exec, s[0:1]
	s_mov_b64 s[0:1], -1
	s_waitcnt vmcnt(7)
	v_lshlrev_b32_e32 v186, 16, v190
	v_and_b32_e32 v187, 0xffff0000, v190
	v_lshlrev_b32_e32 v180, 16, v191
	v_and_b32_e32 v181, 0xffff0000, v191
	v_lshlrev_b32_e32 v188, 16, v192
	v_and_b32_e32 v189, 0xffff0000, v192
	v_lshlrev_b32_e32 v182, 16, v193
	v_and_b32_e32 v183, 0xffff0000, v193
	global_load_dwordx4 v[190:193], v[222:223], off
	v_pk_fma_f32 v[182:183], v[140:141], v[132:133], v[182:183]
	v_pk_fma_f32 v[138:139], v[138:139], v[130:131], v[188:189]
	v_pk_fma_f32 v[144:145], v[144:145], v[136:137], v[180:181]
	v_pk_fma_f32 v[142:143], v[142:143], v[134:135], v[186:187]
	v_cvt_pk_bf16_f32 v140, v138, v139
	v_cvt_pk_bf16_f32 v141, v182, v183
	v_cvt_pk_bf16_f32 v138, v142, v143
	v_cvt_pk_bf16_f32 v139, v144, v145
	global_store_dwordx4 v[184:185], v[138:141], off
	s_nop 0
	v_or_b32_e32 v142, 16, v168
	v_ashrrev_i32_e32 v143, 31, v142
	v_lshlrev_b64 v[142:143], 12, v[142:143]
	v_lshl_add_u64 v[144:145], s[64:65], 0, v[142:143]
	v_lshl_add_u64 v[144:145], v[144:145], 0, v[164:165]
	s_waitcnt vmcnt(8)
	v_lshlrev_b32_e32 v176, 16, v194
	v_and_b32_e32 v177, 0xffff0000, v194
	v_lshlrev_b32_e32 v138, 16, v195
	v_and_b32_e32 v139, 0xffff0000, v195
	v_lshlrev_b32_e32 v180, 16, v196
	v_and_b32_e32 v181, 0xffff0000, v196
	v_lshlrev_b32_e32 v140, 16, v197
	v_and_b32_e32 v141, 0xffff0000, v197
	global_load_dwordx4 v[194:197], v[222:223], off offset:256
	v_pk_fma_f32 v[120:121], v[120:121], v[128:129], v[138:139]
	v_pk_fma_f32 v[118:119], v[118:119], v[126:127], v[176:177]
	v_pk_fma_f32 v[138:139], v[116:117], v[124:125], v[140:141]
	v_pk_fma_f32 v[116:117], v[114:115], v[122:123], v[180:181]
	v_cvt_pk_bf16_f32 v114, v118, v119
	v_cvt_pk_bf16_f32 v115, v120, v121
	v_cvt_pk_bf16_f32 v116, v116, v117
	v_cvt_pk_bf16_f32 v117, v138, v139
	global_store_dwordx4 v[184:185], v[114:117], off offset:256
	s_nop 0
	v_lshl_add_u64 v[118:119], s[52:53], 0, v[142:143]
	v_lshl_add_u64 v[118:119], v[118:119], 0, v[164:165]
	s_waitcnt vmcnt(9)
	v_lshlrev_b32_e32 v120, 16, v198
	v_and_b32_e32 v121, 0xffff0000, v198
	v_lshlrev_b32_e32 v114, 16, v199
	v_and_b32_e32 v115, 0xffff0000, v199
	v_lshlrev_b32_e32 v138, 16, v200
	v_and_b32_e32 v139, 0xffff0000, v200
	v_lshlrev_b32_e32 v116, 16, v201
	v_and_b32_e32 v117, 0xffff0000, v201
	global_load_dwordx4 v[198:201], v[224:225], off
	v_pk_fma_f32 v[112:113], v[112:113], v[136:137], v[114:115]
	v_pk_fma_f32 v[110:111], v[110:111], v[134:135], v[120:121]
	v_pk_fma_f32 v[114:115], v[108:109], v[132:133], v[116:117]
	v_pk_fma_f32 v[108:109], v[106:107], v[130:131], v[138:139]
	v_cvt_pk_bf16_f32 v106, v110, v111
	v_cvt_pk_bf16_f32 v107, v112, v113
	v_cvt_pk_bf16_f32 v108, v108, v109
	v_cvt_pk_bf16_f32 v109, v114, v115
	global_store_dwordx4 v[118:119], v[106:109], off
	s_nop 0
	v_or_b32_e32 v110, 32, v168
	v_ashrrev_i32_e32 v111, 31, v110
	v_lshlrev_b64 v[110:111], 12, v[110:111]
	v_lshl_add_u64 v[112:113], s[64:65], 0, v[110:111]
	v_lshl_add_u64 v[112:113], v[112:113], 0, v[164:165]
	s_waitcnt vmcnt(10)
	v_lshlrev_b32_e32 v114, 16, v202
	v_and_b32_e32 v115, 0xffff0000, v202
	v_lshlrev_b32_e32 v106, 16, v203
	v_and_b32_e32 v107, 0xffff0000, v203
	v_lshlrev_b32_e32 v116, 16, v204
	v_and_b32_e32 v117, 0xffff0000, v204
	v_lshlrev_b32_e32 v108, 16, v205
	v_and_b32_e32 v109, 0xffff0000, v205
	global_load_dwordx4 v[202:205], v[224:225], off offset:256
	v_pk_fma_f32 v[104:105], v[104:105], v[128:129], v[106:107]
	v_pk_fma_f32 v[102:103], v[102:103], v[126:127], v[114:115]
	v_pk_fma_f32 v[106:107], v[100:101], v[124:125], v[108:109]
	v_pk_fma_f32 v[100:101], v[98:99], v[122:123], v[116:117]
	v_cvt_pk_bf16_f32 v98, v102, v103
	v_cvt_pk_bf16_f32 v99, v104, v105
	v_cvt_pk_bf16_f32 v100, v100, v101
	v_cvt_pk_bf16_f32 v101, v106, v107
	global_store_dwordx4 v[118:119], v[98:101], off offset:256
	s_nop 0
	v_lshl_add_u64 v[102:103], s[52:53], 0, v[110:111]
	v_lshl_add_u64 v[102:103], v[102:103], 0, v[164:165]
	s_waitcnt vmcnt(11)
	v_lshlrev_b32_e32 v104, 16, v206
	v_and_b32_e32 v105, 0xffff0000, v206
	v_lshlrev_b32_e32 v98, 16, v207
	v_and_b32_e32 v99, 0xffff0000, v207
	v_lshlrev_b32_e32 v106, 16, v208
	v_and_b32_e32 v107, 0xffff0000, v208
	v_lshlrev_b32_e32 v100, 16, v209
	v_and_b32_e32 v101, 0xffff0000, v209
	global_load_dwordx4 v[206:209], v[226:227], off
	v_pk_fma_f32 v[96:97], v[96:97], v[136:137], v[98:99]
	v_pk_fma_f32 v[94:95], v[94:95], v[134:135], v[104:105]
	v_pk_fma_f32 v[98:99], v[92:93], v[132:133], v[100:101]
	v_pk_fma_f32 v[92:93], v[90:91], v[130:131], v[106:107]
	v_cvt_pk_bf16_f32 v90, v94, v95
	v_cvt_pk_bf16_f32 v91, v96, v97
	v_cvt_pk_bf16_f32 v92, v92, v93
	v_cvt_pk_bf16_f32 v93, v98, v99
	global_store_dwordx4 v[102:103], v[90:93], off
	s_nop 0
	v_or_b32_e32 v94, 48, v168
	v_ashrrev_i32_e32 v95, 31, v94
	v_lshlrev_b64 v[94:95], 12, v[94:95]
	v_lshl_add_u64 v[96:97], s[64:65], 0, v[94:95]
	v_lshl_add_u64 v[96:97], v[96:97], 0, v[164:165]
	s_waitcnt vmcnt(12)
	v_lshlrev_b32_e32 v98, 16, v210
	v_and_b32_e32 v99, 0xffff0000, v210
	v_lshlrev_b32_e32 v90, 16, v211
	v_and_b32_e32 v91, 0xffff0000, v211
	v_lshlrev_b32_e32 v100, 16, v212
	v_and_b32_e32 v101, 0xffff0000, v212
	v_lshlrev_b32_e32 v92, 16, v213
	v_and_b32_e32 v93, 0xffff0000, v213
	global_load_dwordx4 v[210:213], v[226:227], off offset:256
	v_pk_fma_f32 v[88:89], v[88:89], v[128:129], v[90:91]
	v_pk_fma_f32 v[86:87], v[86:87], v[126:127], v[98:99]
	v_pk_fma_f32 v[90:91], v[84:85], v[124:125], v[92:93]
	v_pk_fma_f32 v[84:85], v[82:83], v[122:123], v[100:101]
	v_cvt_pk_bf16_f32 v82, v86, v87
	v_cvt_pk_bf16_f32 v83, v88, v89
	v_cvt_pk_bf16_f32 v84, v84, v85
	v_cvt_pk_bf16_f32 v85, v90, v91
	global_store_dwordx4 v[102:103], v[82:85], off offset:256
	s_nop 0
	v_lshl_add_u64 v[86:87], s[52:53], 0, v[94:95]
	v_lshl_add_u64 v[86:87], v[86:87], 0, v[164:165]
	s_waitcnt vmcnt(13)
	v_lshlrev_b32_e32 v88, 16, v214
	v_and_b32_e32 v89, 0xffff0000, v214
	v_lshlrev_b32_e32 v82, 16, v215
	v_and_b32_e32 v83, 0xffff0000, v215
	v_lshlrev_b32_e32 v90, 16, v216
	v_and_b32_e32 v91, 0xffff0000, v216
	v_lshlrev_b32_e32 v84, 16, v217
	v_and_b32_e32 v85, 0xffff0000, v217
	global_load_dwordx4 v[214:217], v[228:229], off
	v_pk_fma_f32 v[80:81], v[80:81], v[136:137], v[82:83]
	v_pk_fma_f32 v[78:79], v[78:79], v[134:135], v[88:89]
	v_pk_fma_f32 v[82:83], v[76:77], v[132:133], v[84:85]
	v_pk_fma_f32 v[76:77], v[74:75], v[130:131], v[90:91]
	v_cvt_pk_bf16_f32 v74, v78, v79
	v_cvt_pk_bf16_f32 v75, v80, v81
	v_cvt_pk_bf16_f32 v76, v76, v77
	v_cvt_pk_bf16_f32 v77, v82, v83
	global_store_dwordx4 v[86:87], v[74:77], off
	s_nop 0
	v_lshl_add_u64 v[78:79], v[166:167], 0, s[16:17]
	v_lshl_add_u64 v[80:81], s[64:65], 0, v[78:79]
	v_lshl_add_u64 v[80:81], v[80:81], 0, v[164:165]
	s_waitcnt vmcnt(14)
	v_lshlrev_b32_e32 v82, 16, v218
	v_and_b32_e32 v83, 0xffff0000, v218
	v_lshlrev_b32_e32 v74, 16, v219
	v_and_b32_e32 v75, 0xffff0000, v219
	v_lshlrev_b32_e32 v84, 16, v220
	v_and_b32_e32 v85, 0xffff0000, v220
	v_lshlrev_b32_e32 v76, 16, v221
	v_and_b32_e32 v77, 0xffff0000, v221
	global_load_dwordx4 v[218:221], v[228:229], off offset:256
	v_pk_fma_f32 v[72:73], v[72:73], v[128:129], v[74:75]
	v_pk_fma_f32 v[70:71], v[70:71], v[126:127], v[82:83]
	v_pk_fma_f32 v[74:75], v[68:69], v[124:125], v[76:77]
	v_pk_fma_f32 v[68:69], v[66:67], v[122:123], v[84:85]
	v_cvt_pk_bf16_f32 v66, v70, v71
	v_cvt_pk_bf16_f32 v67, v72, v73
	v_cvt_pk_bf16_f32 v68, v68, v69
	v_cvt_pk_bf16_f32 v69, v74, v75
	global_store_dwordx4 v[86:87], v[66:69], off offset:256
	s_nop 0
	v_lshl_add_u64 v[70:71], s[52:53], 0, v[78:79]
	v_lshl_add_u64 v[70:71], v[70:71], 0, v[164:165]
	s_waitcnt vmcnt(15)
	v_lshlrev_b32_e32 v72, 16, v190
	v_and_b32_e32 v73, 0xffff0000, v190
	v_lshlrev_b32_e32 v66, 16, v191
	v_and_b32_e32 v67, 0xffff0000, v191
	v_lshlrev_b32_e32 v74, 16, v192
	v_and_b32_e32 v75, 0xffff0000, v192
	v_lshlrev_b32_e32 v68, 16, v193
	v_and_b32_e32 v69, 0xffff0000, v193
	v_pk_fma_f32 v[64:65], v[64:65], v[136:137], v[66:67]
	v_pk_fma_f32 v[62:63], v[62:63], v[134:135], v[72:73]
	v_pk_fma_f32 v[66:67], v[60:61], v[132:133], v[68:69]
	v_pk_fma_f32 v[60:61], v[58:59], v[130:131], v[74:75]
	v_cvt_pk_bf16_f32 v58, v62, v63
	v_cvt_pk_bf16_f32 v59, v64, v65
	v_cvt_pk_bf16_f32 v60, v60, v61
	v_cvt_pk_bf16_f32 v61, v66, v67
	global_store_dwordx4 v[70:71], v[58:61], off
	s_nop 0
	v_lshl_add_u64 v[62:63], v[166:167], 0, s[18:19]
	v_lshl_add_u64 v[64:65], s[64:65], 0, v[62:63]
	v_lshl_add_u64 v[64:65], v[64:65], 0, v[164:165]
	s_waitcnt vmcnt(14)
	v_lshlrev_b32_e32 v66, 16, v194
	v_and_b32_e32 v67, 0xffff0000, v194
	v_lshlrev_b32_e32 v58, 16, v195
	v_and_b32_e32 v59, 0xffff0000, v195
	v_lshlrev_b32_e32 v68, 16, v196
	v_and_b32_e32 v69, 0xffff0000, v196
	v_lshlrev_b32_e32 v60, 16, v197
	v_and_b32_e32 v61, 0xffff0000, v197
	v_pk_fma_f32 v[56:57], v[56:57], v[128:129], v[58:59]
	v_pk_fma_f32 v[54:55], v[54:55], v[126:127], v[66:67]
	v_pk_fma_f32 v[58:59], v[52:53], v[124:125], v[60:61]
	v_pk_fma_f32 v[52:53], v[50:51], v[122:123], v[68:69]
	v_cvt_pk_bf16_f32 v50, v54, v55
	v_cvt_pk_bf16_f32 v51, v56, v57
	v_cvt_pk_bf16_f32 v52, v52, v53
	v_cvt_pk_bf16_f32 v53, v58, v59
	global_store_dwordx4 v[70:71], v[50:53], off offset:256
	s_nop 0
	v_lshl_add_u64 v[54:55], s[52:53], 0, v[62:63]
	v_lshl_add_u64 v[54:55], v[54:55], 0, v[164:165]
	s_waitcnt vmcnt(13)
	v_lshlrev_b32_e32 v56, 16, v198
	v_and_b32_e32 v57, 0xffff0000, v198
	v_lshlrev_b32_e32 v50, 16, v199
	v_and_b32_e32 v51, 0xffff0000, v199
	v_lshlrev_b32_e32 v58, 16, v200
	v_and_b32_e32 v59, 0xffff0000, v200
	v_lshlrev_b32_e32 v52, 16, v201
	v_and_b32_e32 v53, 0xffff0000, v201
	v_pk_fma_f32 v[48:49], v[48:49], v[136:137], v[50:51]
	v_pk_fma_f32 v[46:47], v[46:47], v[134:135], v[56:57]
	v_pk_fma_f32 v[50:51], v[44:45], v[132:133], v[52:53]
	v_pk_fma_f32 v[44:45], v[42:43], v[130:131], v[58:59]
	v_cvt_pk_bf16_f32 v42, v46, v47
	v_cvt_pk_bf16_f32 v43, v48, v49
	v_cvt_pk_bf16_f32 v44, v44, v45
	v_cvt_pk_bf16_f32 v45, v50, v51
	global_store_dwordx4 v[54:55], v[42:45], off
	s_nop 0
	v_lshl_add_u64 v[46:47], v[166:167], 0, s[20:21]
	v_lshl_add_u64 v[48:49], s[64:65], 0, v[46:47]
	v_lshl_add_u64 v[48:49], v[48:49], 0, v[164:165]
	s_waitcnt vmcnt(12)
	v_lshlrev_b32_e32 v50, 16, v202
	v_and_b32_e32 v51, 0xffff0000, v202
	v_lshlrev_b32_e32 v42, 16, v203
	v_and_b32_e32 v43, 0xffff0000, v203
	v_lshlrev_b32_e32 v52, 16, v204
	v_and_b32_e32 v53, 0xffff0000, v204
	v_lshlrev_b32_e32 v44, 16, v205
	v_and_b32_e32 v45, 0xffff0000, v205
	v_pk_fma_f32 v[40:41], v[40:41], v[128:129], v[42:43]
	v_pk_fma_f32 v[38:39], v[38:39], v[126:127], v[50:51]
	v_pk_fma_f32 v[42:43], v[36:37], v[124:125], v[44:45]
	v_pk_fma_f32 v[36:37], v[34:35], v[122:123], v[52:53]
	v_cvt_pk_bf16_f32 v34, v38, v39
	v_cvt_pk_bf16_f32 v35, v40, v41
	v_cvt_pk_bf16_f32 v36, v36, v37
	v_cvt_pk_bf16_f32 v37, v42, v43
	global_store_dwordx4 v[54:55], v[34:37], off offset:256
	s_nop 0
	v_lshl_add_u64 v[38:39], s[52:53], 0, v[46:47]
	v_lshl_add_u64 v[38:39], v[38:39], 0, v[164:165]
	s_waitcnt vmcnt(11)
	v_lshlrev_b32_e32 v40, 16, v206
	v_and_b32_e32 v41, 0xffff0000, v206
	v_lshlrev_b32_e32 v34, 16, v207
	v_and_b32_e32 v35, 0xffff0000, v207
	v_lshlrev_b32_e32 v42, 16, v208
	v_and_b32_e32 v43, 0xffff0000, v208
	v_lshlrev_b32_e32 v36, 16, v209
	v_and_b32_e32 v37, 0xffff0000, v209
	v_pk_fma_f32 v[32:33], v[32:33], v[136:137], v[34:35]
	v_pk_fma_f32 v[30:31], v[30:31], v[134:135], v[40:41]
	v_pk_fma_f32 v[34:35], v[28:29], v[132:133], v[36:37]
	v_pk_fma_f32 v[28:29], v[26:27], v[130:131], v[42:43]
	v_cvt_pk_bf16_f32 v26, v30, v31
	v_cvt_pk_bf16_f32 v27, v32, v33
	v_cvt_pk_bf16_f32 v28, v28, v29
	v_cvt_pk_bf16_f32 v29, v34, v35
	global_store_dwordx4 v[38:39], v[26:29], off
	s_nop 0
	v_lshl_add_u64 v[30:31], v[166:167], 0, s[22:23]
	v_lshl_add_u64 v[32:33], s[64:65], 0, v[30:31]
	v_lshl_add_u64 v[32:33], v[32:33], 0, v[164:165]
	s_waitcnt vmcnt(10)
	v_lshlrev_b32_e32 v34, 16, v210
	v_and_b32_e32 v35, 0xffff0000, v210
	v_lshlrev_b32_e32 v26, 16, v211
	v_and_b32_e32 v27, 0xffff0000, v211
	v_lshlrev_b32_e32 v36, 16, v212
	v_and_b32_e32 v37, 0xffff0000, v212
	v_lshlrev_b32_e32 v28, 16, v213
	v_and_b32_e32 v29, 0xffff0000, v213
	v_pk_fma_f32 v[24:25], v[24:25], v[128:129], v[26:27]
	v_pk_fma_f32 v[22:23], v[22:23], v[126:127], v[34:35]
	v_pk_fma_f32 v[26:27], v[20:21], v[124:125], v[28:29]
	v_pk_fma_f32 v[20:21], v[18:19], v[122:123], v[36:37]
	v_cvt_pk_bf16_f32 v18, v22, v23
	v_cvt_pk_bf16_f32 v19, v24, v25
	v_cvt_pk_bf16_f32 v20, v20, v21
	v_cvt_pk_bf16_f32 v21, v26, v27
	global_store_dwordx4 v[38:39], v[18:21], off offset:256
	s_nop 0
	v_lshl_add_u64 v[22:23], s[52:53], 0, v[30:31]
	v_lshl_add_u64 v[22:23], v[22:23], 0, v[164:165]
	s_waitcnt vmcnt(9)
	v_lshlrev_b32_e32 v24, 16, v214
	v_and_b32_e32 v25, 0xffff0000, v214
	v_lshlrev_b32_e32 v18, 16, v215
	v_and_b32_e32 v19, 0xffff0000, v215
	v_lshlrev_b32_e32 v26, 16, v216
	v_and_b32_e32 v27, 0xffff0000, v216
	v_lshlrev_b32_e32 v20, 16, v217
	v_and_b32_e32 v21, 0xffff0000, v217
	v_pk_fma_f32 v[16:17], v[16:17], v[136:137], v[18:19]
	v_pk_fma_f32 v[14:15], v[14:15], v[134:135], v[24:25]
	v_pk_fma_f32 v[18:19], v[12:13], v[132:133], v[20:21]
	v_pk_fma_f32 v[12:13], v[10:11], v[130:131], v[26:27]
	v_cvt_pk_bf16_f32 v10, v14, v15
	v_cvt_pk_bf16_f32 v11, v16, v17
	v_cvt_pk_bf16_f32 v12, v12, v13
	v_cvt_pk_bf16_f32 v13, v18, v19
	global_store_dwordx4 v[22:23], v[10:13], off
	s_nop 0
	s_waitcnt vmcnt(8)
	v_lshlrev_b32_e32 v14, 16, v218
	v_and_b32_e32 v15, 0xffff0000, v218
	v_lshlrev_b32_e32 v10, 16, v219
	v_and_b32_e32 v11, 0xffff0000, v219
	v_lshlrev_b32_e32 v16, 16, v220
	v_and_b32_e32 v17, 0xffff0000, v220
	v_lshlrev_b32_e32 v12, 16, v221
	v_and_b32_e32 v13, 0xffff0000, v221
	v_pk_fma_f32 v[8:9], v[8:9], v[128:129], v[10:11]
	v_pk_fma_f32 v[6:7], v[6:7], v[126:127], v[14:15]
	v_pk_fma_f32 v[10:11], v[4:5], v[124:125], v[12:13]
	v_pk_fma_f32 v[4:5], v[2:3], v[122:123], v[16:17]
	v_cvt_pk_bf16_f32 v2, v6, v7
	v_cvt_pk_bf16_f32 v3, v8, v9
	v_cvt_pk_bf16_f32 v4, v4, v5
	v_cvt_pk_bf16_f32 v5, v10, v11
	global_store_dwordx4 v[22:23], v[2:5], off offset:256
	s_cbranch_vccnz .LBB0_1276
	s_andn2_b64 vcc, exec, s[6:7]
	s_cbranch_vccnz .LBB0_1275
	s_barrier
	s_branch .LBB0_1275
